# grid barrier tail rewritten: XCD last arriver adds to TOP without waiting for the return, all workgroups poll TOP >= (gen+1)*nx
# baseline (speedup 1.0000x reference)
; __device__ __forceinline__ unsigned xb_ld(unsigned* p)              { return __hip_atomic_load(p, __ATOMIC_RELAXED, __HIP_MEMORY_SCOPE_AGENT); }
; __device__ __forceinline__ unsigned xb_add(unsigned* p, unsigned v) { return __hip_atomic_fetch_add(p, v, __ATOMIC_RELAXED, __HIP_MEMORY_SCOPE_AGENT); }
; #define XB_SPIN(cond, bar) do { unsigned _sp = 0; while (cond) { __builtin_amdgcn_s_sleep(1); \
;     if ((++_sp & 255u) == 0u) { if (xb_ld(&(bar)[XB_TMO])) break; if (_sp > XB_SPIN_CAP) { atomicAdd(&(bar)[XB_TMO], 1u); break; } } } } while (0)
; __device__ __forceinline__ void xcd_barrier(const XcdBarrier& b) {
;     ...
;         const unsigned old = xb_add(&bar[XB_XSUB(b.x)], 1u);
;         const unsigned gen = old / nloc;
;         if (old + 1u == (gen + 1u) * nloc) {
;             __builtin_amdgcn_fence(__ATOMIC_RELEASE, "agent");
;             asm volatile("s_waitcnt vmcnt(0)" ::: "memory");
;             const unsigned og = xb_add(&bar[XB_TOP], 1u);
;             const unsigned tg = og / nx;
;             if (og + 1u == (tg + 1u) * nx) xb_add(&bar[XB_TOPGEN], 1u);
;             else XB_SPIN(xb_ld(&bar[XB_TOPGEN]) == tg, bar);
;             __builtin_amdgcn_fence(__ATOMIC_ACQUIRE, "agent");
;             xb_add(&bar[XB_XGEN(b.x)], 1u);
;             asm volatile("s_waitcnt vmcnt(0)" ::: "memory");
;         } else {
;             XB_SPIN(xb_ld(&bar[XB_XGEN(b.x)]) == gen, bar);
.LBB0_49:
	s_or_b64 exec, exec, s[14:15]
	v_cvt_f32_u32_e32 v5, v3
	s_waitcnt vmcnt(0)
	v_readfirstlane_b32 s3, v4
	v_sub_u32_e32 v4, 0, v3
	v_rcp_iflag_f32_e32 v5, v5
	v_add_u32_e32 v6, s3, v2
	v_mul_f32_e32 v5, 0x4f7ffffe, v5
	v_cvt_u32_f32_e32 v5, v5
	v_mul_lo_u32 v2, v4, v5
	v_mul_hi_u32 v2, v5, v2
	v_add_u32_e32 v2, v5, v2
	v_mul_hi_u32 v2, v6, v2
	v_mul_lo_u32 v4, v2, v3
	v_sub_u32_e32 v4, v6, v4
	v_add_u32_e32 v5, 1, v2
	v_cmp_ge_u32_e32 vcc, v4, v3
	s_nop 1
	v_cndmask_b32_e32 v2, v2, v5, vcc
	v_sub_u32_e32 v5, v4, v3
	v_cndmask_b32_e32 v4, v4, v5, vcc
	v_add_u32_e32 v5, 1, v2
	v_cmp_ge_u32_e32 vcc, v4, v3
	v_add_u32_e32 v4, 1, v6
	s_nop 0
	v_cndmask_b32_e32 v2, v2, v5, vcc
	v_mul_lo_u32 v5, v3, v2
	v_add_u32_e32 v3, v5, v3
	s_waitcnt lgkmcnt(0)
	v_add_u32_e32 v2, 1, v2
	v_mul_lo_u32 v2, v2, v1
	v_cmp_ne_u32_e32 vcc, v4, v3
	s_cbranch_vccnz .Lgb0_poll
	buffer_wbl2 sc1
	s_waitcnt vmcnt(0)
	v_mov_b32_e32 v4, 0x3400
	v_mov_b32_e32 v5, 1
	global_atomic_add v4, v5, s[74:75]
.Lgb0_poll:
	v_mov_b32_e32 v4, 0x3400
	s_mov_b32 s3, 0
.Lgb0_loop:
	global_load_dword v5, v4, s[74:75] sc1
	s_waitcnt vmcnt(0)
	v_cmp_ge_u32_e32 vcc, v5, v2
	s_cbranch_vccnz .Lgb0_done
	s_sleep 1
	s_add_i32 s3, s3, 1
	s_cmp_lt_u32 s3, 0x40000
	s_cbranch_scc1 .Lgb0_loop
.Lgb0_done:
	buffer_inv sc1
	s_waitcnt vmcnt(0)

; __device__ __forceinline__ unsigned xb_ld(unsigned* p)              { return __hip_atomic_load(p, __ATOMIC_RELAXED, __HIP_MEMORY_SCOPE_AGENT); }
; __device__ __forceinline__ unsigned xb_add(unsigned* p, unsigned v) { return __hip_atomic_fetch_add(p, v, __ATOMIC_RELAXED, __HIP_MEMORY_SCOPE_AGENT); }
; #define XB_SPIN(cond, bar) do { unsigned _sp = 0; while (cond) { __builtin_amdgcn_s_sleep(1); \
;     if ((++_sp & 255u) == 0u) { if (xb_ld(&(bar)[XB_TMO])) break; if (_sp > XB_SPIN_CAP) { atomicAdd(&(bar)[XB_TMO], 1u); break; } } } } while (0)
; __device__ __forceinline__ void xcd_barrier(const XcdBarrier& b) {
;     ...
;         const unsigned old = xb_add(&bar[XB_XSUB(b.x)], 1u);
;         const unsigned gen = old / nloc;
;         if (old + 1u == (gen + 1u) * nloc) {
;             __builtin_amdgcn_fence(__ATOMIC_RELEASE, "agent");
;             asm volatile("s_waitcnt vmcnt(0)" ::: "memory");
;             const unsigned og = xb_add(&bar[XB_TOP], 1u);
;             const unsigned tg = og / nx;
;             if (og + 1u == (tg + 1u) * nx) xb_add(&bar[XB_TOPGEN], 1u);
;             else XB_SPIN(xb_ld(&bar[XB_TOPGEN]) == tg, bar);
.LBB0_474:
	s_or_b64 exec, exec, s[12:13]
	v_cvt_f32_u32_e32 v5, v3
	s_waitcnt vmcnt(0)
	v_readfirstlane_b32 s3, v4
	v_sub_u32_e32 v4, 0, v3
	v_rcp_iflag_f32_e32 v5, v5
	v_add_u32_e32 v6, s3, v2
	v_mul_f32_e32 v5, 0x4f7ffffe, v5
	v_cvt_u32_f32_e32 v5, v5
	v_mul_lo_u32 v2, v4, v5
	v_mul_hi_u32 v2, v5, v2
	v_add_u32_e32 v2, v5, v2
	v_mul_hi_u32 v2, v6, v2
	v_mul_lo_u32 v4, v2, v3
	v_sub_u32_e32 v4, v6, v4
	v_add_u32_e32 v5, 1, v2
	v_cmp_ge_u32_e32 vcc, v4, v3
	s_nop 1
	v_cndmask_b32_e32 v2, v2, v5, vcc
	v_sub_u32_e32 v5, v4, v3
	v_cndmask_b32_e32 v4, v4, v5, vcc
	v_add_u32_e32 v5, 1, v2
	v_cmp_ge_u32_e32 vcc, v4, v3
	v_add_u32_e32 v4, 1, v6
	s_nop 0
	v_cndmask_b32_e32 v2, v2, v5, vcc
	v_mul_lo_u32 v5, v3, v2
	v_add_u32_e32 v3, v5, v3
	s_waitcnt lgkmcnt(0)
	v_add_u32_e32 v2, 1, v2
	v_mul_lo_u32 v2, v2, v1
	v_cmp_ne_u32_e32 vcc, v4, v3
	s_cbranch_vccnz .Lgb5_poll
	buffer_wbl2 sc1
	s_waitcnt vmcnt(0)
	v_mov_b32_e32 v4, 0x3400
	v_mov_b32_e32 v5, 1
	global_atomic_add v4, v5, s[74:75]
